# unit header: hardcoded gsz=8 (no runtime division); kvb epilogue regenerated with hoisted loads and counted vmcnt
# speedup vs baseline: 1.0137x; 1.0009x over previous
;     __host__ __device__ bool next(int i, Unit& u) const {
;         const long L = (long)i * G + c; if (L >= nwg) return false;
;         int wgid = (int)L; { const int q = nwg / NXCD, r = nwg % NXCD, xcd = wgid % NXCD, off = wgid / NXCD; wgid = (xcd < r ? xcd * (q + 1) : r * (q + 1) + (xcd - r) * q) + off; }
;         const int nig = WGM * nN, gid = wgid / nig, fm = gid * WGM, gsz = (nM - fm) < WGM ? (nM - fm) : WGM;
;         u.pm = fm + ((wgid % nig) % gsz); u.pn = (wgid % nig) / gsz; return true;
.LBB0_499:
	s_add_i32 s43, s30, 1
	v_readlane_b32 s10, v254, 55
	s_mul_i32 s10, s43, s10
	s_mul_hi_u32 s11, s43, s90
	s_add_i32 s11, s11, s10
	s_mul_i32 s10, s43, s90
	s_add_u32 s10, s10, s91
	v_readlane_b32 s12, v254, 56
	s_addc_u32 s11, s11, s12
	v_readlane_b32 s12, v254, 32
	v_readlane_b32 s13, v254, 33
	s_nop 1
	v_mov_b64_e32 v[2:3], s[12:13]
	v_cmp_ge_i64_e32 vcc, s[10:11], v[2:3]
	v_cmp_lt_i64_e64 s[12:13], s[10:11], v[2:3]
	s_cbranch_vccnz .LBB0_501
	s_ashr_i32 s11, s10, 31
	s_lshr_b32 s11, s11, 29
	s_add_i32 s11, s10, s11
	s_ashr_i32 s16, s11, 3
	s_and_b32 s11, s11, -8
	s_sub_i32 s10, s10, s11
	s_lshr_b32 s11, s10, 31
	v_readlane_b32 s20, v254, 36
	s_or_b32 s11, s20, s11
	s_mul_i32 s10, s11, s10
	s_add_i32 s10, s10, s16
	s_ashr_i32 s11, s10, 31
	v_readlane_b32 s16, v254, 37
	s_xor_b32 s11, s11, s16
	s_abs_i32 s16, s10
	v_readlane_b32 s17, v254, 38
	s_mul_hi_u32 s17, s16, s17
	s_mul_i32 s18, s17, s49
	s_sub_i32 s16, s16, s18
	s_add_i32 s18, s17, 1
	s_sub_i32 s19, s16, s49
	s_cmp_ge_u32 s16, s49
	s_cselect_b32 s17, s18, s17
	s_cselect_b32 s16, s19, s16
	s_add_i32 s18, s17, 1
	s_cmp_ge_u32 s16, s49
	s_cselect_b32 s16, s18, s17
	s_xor_b32 s16, s16, s11
	s_sub_i32 s11, s16, s11
	s_lshl_b32 s16, s11, 3
	s_mul_i32 s11, s11, s20
	s_sub_i32 s10, s10, s11
	s_lshr_b32 s38, s10, 3
	s_and_b32 s10, s10, 7
	s_add_i32 s80, s10, s16

; __device__ __forceinline__ u32x4 pack8(const f32x4& a, const f32x4& b, float sc) { u32x4 w; w[0] = pk2(a[0] * sc, a[1] * sc); w[1] = pk2(a[2] * sc, a[3] * sc); w[2] = pk2(b[0] * sc, b[1] * sc); w[3] = pk2(b[2] * sc, b[3] * sc); return w; }
; __device__ __forceinline__ void epi_kvb(const MixBufs B, const f32x4 (&acc)[2][2][4][2], const Unit& u, int wr, int wc, int fr, int fq) {
;     const int pn = u.pn, c8 = wc * 32 + fq * 8;
;     bf16_t* dst = pn < 4 ? mKM(B) : mVM(B); const int hp = pn & 3;
;     f32x4 sq[2];
;     sq[0] = *(const f32x4*)(mSSKV(B) + (size_t)opaque(EPI_ROW(0)) * 4);
; #pragma unroll
;     for (int it = 0; it < 8; ++it) {
;         const int ai = it >> 2, m = it & 3; const int r = opaque(EPI_ROW(it));
;         if (it + 1 < 8) sq[(it + 1) & 1] = *(const f32x4*)(mSSKV(B) + (size_t)opaque(EPI_ROW(it + 1)) * 4);
;         const f32x4 sv = sq[it & 1];
;         const float rs = rsqrtf(((sv[0] + sv[1]) + (sv[2] + sv[3])) * (1.0f / 256) + RMS_EPS);
;         *(u32x4*)(dst + (size_t)r * 1024 + (2 * hp) * 128 + c8) = pack8(acc[ai][0][m][0], acc[ai][0][m][1], rs);
;         *(u32x4*)(dst + (size_t)r * 1024 + (2 * hp + 1) * 128 + c8) = pack8(acc[ai][1][m][0], acc[ai][1][m][1], rs);
;         asm volatile("" ::: "memory");
;     }
; }
.LBB0_520:
	s_lshl_b32 s2, s30, 10
	s_and_b32 s2, s2, 0x400
	s_add_i32 s39, s2, 0
	s_add_i32 s39, s39, 0x20000
	s_cmp_lt_i32 s88, 2
	s_mov_b64 s[2:3], -1
	s_cbranch_scc1 .LBB0_733
	s_cmp_lt_i32 s88, 3
	s_cbranch_scc1 .LBB0_579
	s_cmp_lg_u32 s88, 3
	s_cbranch_scc0 .LBB0_524
	s_cmp_lt_i32 s77, 4
	s_mov_b32 s12, 0x93c1000
	s_mov_b64 s[2:3], s[96:97]
	s_cselect_b32 s12, s12, 0xb3c1000
	s_add_u32 s12, s2, s12
	s_addc_u32 s13, s3, 0
	s_add_u32 s14, s2, 0x19680000
	s_addc_u32 s15, s3, 0
	s_lshl_b32 s16, s81, 8
	s_lshl_b32 s2, s77, 9
	s_and_b32 s2, s2, 0x600
	s_add_u32 s2, s12, s2
	s_addc_u32 s3, s13, 0
	s_add_u32 s2, s2, 0x17e00000
	s_addc_u32 s3, s3, 0
	s_waitcnt lgkmcnt(0)
	v_add_u32_e32 v130, s16, v193
	v_lshlrev_b32_e32 v131, 4, v130
	v_lshlrev_b32_e32 v130, 11, v130
	v_lshl_add_u32 v130, v194, 1, v130
	global_load_dwordx4 v[132:135], v131, s[14:15]
	global_load_dwordx4 v[136:139], v131, s[14:15] offset:256
	global_load_dwordx4 v[140:143], v131, s[14:15] offset:512
	global_load_dwordx4 v[144:147], v131, s[14:15] offset:768
	global_load_dwordx4 v[148:151], v131, s[14:15] offset:2048
	global_load_dwordx4 v[152:155], v131, s[14:15] offset:2304
	global_load_dwordx4 v[156:159], v131, s[14:15] offset:2560
	global_load_dwordx4 v[160:163], v131, s[14:15] offset:2816
	s_waitcnt vmcnt(7)
	v_add_f32_e32 v164, v132, v133
	v_add_f32_e32 v165, v134, v135
	v_add_f32_e32 v164, v164, v165
	v_fmamk_f32 v164, v164, 0x3b800000, v222
	v_mul_f32_e32 v165, 0x4b800000, v164
	v_cmp_gt_f32_e32 vcc, s92, v164
	s_nop 1
	v_cndmask_b32_e32 v164, v164, v165, vcc
	v_rsq_f32_e32 v164, v164
	s_nop 0
	v_mul_f32_e32 v165, 0x45800000, v164
	v_cndmask_b32_e32 v166, v164, v165, vcc
	v_pk_mul_f32 v[126:127], v[126:127], v[166:167] op_sel_hi:[1,0]
	v_pk_mul_f32 v[128:129], v[128:129], v[166:167] op_sel_hi:[1,0]
	v_pk_mul_f32 v[118:119], v[118:119], v[166:167] op_sel_hi:[1,0]
	v_pk_mul_f32 v[120:121], v[120:121], v[166:167] op_sel_hi:[1,0]
	v_cvt_pk_bf16_f32 v168, v126, v127
	v_cvt_pk_bf16_f32 v169, v128, v129
	v_cvt_pk_bf16_f32 v170, v118, v119
	v_cvt_pk_bf16_f32 v171, v120, v121
	global_store_dwordx4 v130, v[168:171], s[2:3]
	v_pk_mul_f32 v[122:123], v[122:123], v[166:167] op_sel_hi:[1,0]
	v_pk_mul_f32 v[124:125], v[124:125], v[166:167] op_sel_hi:[1,0]
	v_pk_mul_f32 v[114:115], v[114:115], v[166:167] op_sel_hi:[1,0]
	v_pk_mul_f32 v[116:117], v[116:117], v[166:167] op_sel_hi:[1,0]
	v_cvt_pk_bf16_f32 v172, v122, v123
	v_cvt_pk_bf16_f32 v173, v124, v125
	v_cvt_pk_bf16_f32 v174, v114, v115
	v_cvt_pk_bf16_f32 v175, v116, v117
	global_store_dwordx4 v130, v[172:175], s[2:3] offset:256
	s_waitcnt vmcnt(8)
	v_add_f32_e32 v164, v136, v137
	v_add_f32_e32 v165, v138, v139
	v_add_f32_e32 v164, v164, v165
	v_fmamk_f32 v164, v164, 0x3b800000, v222
	v_mul_f32_e32 v165, 0x4b800000, v164
	v_cmp_gt_f32_e32 vcc, s92, v164
	s_nop 1
	v_cndmask_b32_e32 v164, v164, v165, vcc
	v_rsq_f32_e32 v164, v164
	s_nop 0
	v_mul_f32_e32 v165, 0x45800000, v164
	v_cndmask_b32_e32 v166, v164, v165, vcc
	v_add_u32_e32 v131, 0x8000, v130
	v_pk_mul_f32 v[110:111], v[110:111], v[166:167] op_sel_hi:[1,0]
	v_pk_mul_f32 v[112:113], v[112:113], v[166:167] op_sel_hi:[1,0]
	v_pk_mul_f32 v[102:103], v[102:103], v[166:167] op_sel_hi:[1,0]
	v_pk_mul_f32 v[104:105], v[104:105], v[166:167] op_sel_hi:[1,0]
	v_cvt_pk_bf16_f32 v176, v110, v111
	v_cvt_pk_bf16_f32 v177, v112, v113
	v_cvt_pk_bf16_f32 v178, v102, v103
	v_cvt_pk_bf16_f32 v179, v104, v105
	global_store_dwordx4 v131, v[176:179], s[2:3]
	v_pk_mul_f32 v[106:107], v[106:107], v[166:167] op_sel_hi:[1,0]
	v_pk_mul_f32 v[108:109], v[108:109], v[166:167] op_sel_hi:[1,0]
	v_pk_mul_f32 v[98:99], v[98:99], v[166:167] op_sel_hi:[1,0]
	v_pk_mul_f32 v[100:101], v[100:101], v[166:167] op_sel_hi:[1,0]
	v_cvt_pk_bf16_f32 v200, v106, v107
	v_cvt_pk_bf16_f32 v201, v108, v109
	v_cvt_pk_bf16_f32 v202, v98, v99
	v_cvt_pk_bf16_f32 v203, v100, v101
	global_store_dwordx4 v131, v[200:203], s[2:3] offset:256
	s_waitcnt vmcnt(9)
	v_add_f32_e32 v164, v140, v141
	v_add_f32_e32 v165, v142, v143
	v_add_f32_e32 v164, v164, v165
	v_fmamk_f32 v164, v164, 0x3b800000, v222
	v_mul_f32_e32 v165, 0x4b800000, v164
	v_cmp_gt_f32_e32 vcc, s92, v164
	s_nop 1
	v_cndmask_b32_e32 v164, v164, v165, vcc
	v_rsq_f32_e32 v164, v164
	s_nop 0
	v_mul_f32_e32 v165, 0x45800000, v164
	v_cndmask_b32_e32 v166, v164, v165, vcc
	v_add_u32_e32 v131, 0x10000, v130
	v_pk_mul_f32 v[94:95], v[94:95], v[166:167] op_sel_hi:[1,0]
	v_pk_mul_f32 v[96:97], v[96:97], v[166:167] op_sel_hi:[1,0]
	v_pk_mul_f32 v[86:87], v[86:87], v[166:167] op_sel_hi:[1,0]
	v_pk_mul_f32 v[88:89], v[88:89], v[166:167] op_sel_hi:[1,0]
	v_cvt_pk_bf16_f32 v168, v94, v95
	v_cvt_pk_bf16_f32 v169, v96, v97
	v_cvt_pk_bf16_f32 v170, v86, v87
	v_cvt_pk_bf16_f32 v171, v88, v89
	global_store_dwordx4 v131, v[168:171], s[2:3]
	v_pk_mul_f32 v[90:91], v[90:91], v[166:167] op_sel_hi:[1,0]
	v_pk_mul_f32 v[92:93], v[92:93], v[166:167] op_sel_hi:[1,0]
	v_pk_mul_f32 v[82:83], v[82:83], v[166:167] op_sel_hi:[1,0]
	v_pk_mul_f32 v[84:85], v[84:85], v[166:167] op_sel_hi:[1,0]
	v_cvt_pk_bf16_f32 v172, v90, v91
	v_cvt_pk_bf16_f32 v173, v92, v93
	v_cvt_pk_bf16_f32 v174, v82, v83
	v_cvt_pk_bf16_f32 v175, v84, v85
	global_store_dwordx4 v131, v[172:175], s[2:3] offset:256
	s_waitcnt vmcnt(10)
; __device__ __forceinline__ u32x4 pack8(const f32x4& a, const f32x4& b, float sc) { u32x4 w; w[0] = pk2(a[0] * sc, a[1] * sc); w[1] = pk2(a[2] * sc, a[3] * sc); w[2] = pk2(b[0] * sc, b[1] * sc); w[3] = pk2(b[2] * sc, b[3] * sc); return w; }
; __device__ __forceinline__ void epi_kvb(const MixBufs B, const f32x4 (&acc)[2][2][4][2], const Unit& u, int wr, int wc, int fr, int fq) {
;     ...
; #pragma unroll
;     for (int it = 0; it < 8; ++it) {
;         const int ai = it >> 2, m = it & 3; const int r = opaque(EPI_ROW(it));
;         if (it + 1 < 8) sq[(it + 1) & 1] = *(const f32x4*)(mSSKV(B) + (size_t)opaque(EPI_ROW(it + 1)) * 4);
;         const f32x4 sv = sq[it & 1];
;         const float rs = rsqrtf(((sv[0] + sv[1]) + (sv[2] + sv[3])) * (1.0f / 256) + RMS_EPS);
;         *(u32x4*)(dst + (size_t)r * 1024 + (2 * hp) * 128 + c8) = pack8(acc[ai][0][m][0], acc[ai][0][m][1], rs);
;         *(u32x4*)(dst + (size_t)r * 1024 + (2 * hp + 1) * 128 + c8) = pack8(acc[ai][1][m][0], acc[ai][1][m][1], rs);
;         asm volatile("" ::: "memory");
;     }
	v_add_f32_e32 v164, v144, v145
	v_add_f32_e32 v165, v146, v147
	v_add_f32_e32 v164, v164, v165
	v_fmamk_f32 v164, v164, 0x3b800000, v222
	v_mul_f32_e32 v165, 0x4b800000, v164
	v_cmp_gt_f32_e32 vcc, s92, v164
	s_nop 1
	v_cndmask_b32_e32 v164, v164, v165, vcc
	v_rsq_f32_e32 v164, v164
	s_nop 0
	v_mul_f32_e32 v165, 0x45800000, v164
	v_cndmask_b32_e32 v166, v164, v165, vcc
	v_add_u32_e32 v131, 0x18000, v130
	v_pk_mul_f32 v[78:79], v[78:79], v[166:167] op_sel_hi:[1,0]
	v_pk_mul_f32 v[80:81], v[80:81], v[166:167] op_sel_hi:[1,0]
	v_pk_mul_f32 v[70:71], v[70:71], v[166:167] op_sel_hi:[1,0]
	v_pk_mul_f32 v[72:73], v[72:73], v[166:167] op_sel_hi:[1,0]
	v_cvt_pk_bf16_f32 v176, v78, v79
	v_cvt_pk_bf16_f32 v177, v80, v81
	v_cvt_pk_bf16_f32 v178, v70, v71
	v_cvt_pk_bf16_f32 v179, v72, v73
	global_store_dwordx4 v131, v[176:179], s[2:3]
	v_pk_mul_f32 v[74:75], v[74:75], v[166:167] op_sel_hi:[1,0]
	v_pk_mul_f32 v[76:77], v[76:77], v[166:167] op_sel_hi:[1,0]
	v_pk_mul_f32 v[66:67], v[66:67], v[166:167] op_sel_hi:[1,0]
	v_pk_mul_f32 v[68:69], v[68:69], v[166:167] op_sel_hi:[1,0]
	v_cvt_pk_bf16_f32 v200, v74, v75
	v_cvt_pk_bf16_f32 v201, v76, v77
	v_cvt_pk_bf16_f32 v202, v66, v67
	v_cvt_pk_bf16_f32 v203, v68, v69
	global_store_dwordx4 v131, v[200:203], s[2:3] offset:256
	s_waitcnt vmcnt(11)
	v_add_f32_e32 v164, v148, v149
	v_add_f32_e32 v165, v150, v151
	v_add_f32_e32 v164, v164, v165
	v_fmamk_f32 v164, v164, 0x3b800000, v222
	v_mul_f32_e32 v165, 0x4b800000, v164
	v_cmp_gt_f32_e32 vcc, s92, v164
	s_nop 1
	v_cndmask_b32_e32 v164, v164, v165, vcc
	v_rsq_f32_e32 v164, v164
	s_nop 0
	v_mul_f32_e32 v165, 0x45800000, v164
	v_cndmask_b32_e32 v166, v164, v165, vcc
	v_add_u32_e32 v131, 0x40000, v130
	v_pk_mul_f32 v[62:63], v[62:63], v[166:167] op_sel_hi:[1,0]
	v_pk_mul_f32 v[64:65], v[64:65], v[166:167] op_sel_hi:[1,0]
	v_pk_mul_f32 v[54:55], v[54:55], v[166:167] op_sel_hi:[1,0]
	v_pk_mul_f32 v[56:57], v[56:57], v[166:167] op_sel_hi:[1,0]
	v_cvt_pk_bf16_f32 v168, v62, v63
	v_cvt_pk_bf16_f32 v169, v64, v65
	v_cvt_pk_bf16_f32 v170, v54, v55
	v_cvt_pk_bf16_f32 v171, v56, v57
	global_store_dwordx4 v131, v[168:171], s[2:3]
	v_pk_mul_f32 v[58:59], v[58:59], v[166:167] op_sel_hi:[1,0]
	v_pk_mul_f32 v[60:61], v[60:61], v[166:167] op_sel_hi:[1,0]
	v_pk_mul_f32 v[50:51], v[50:51], v[166:167] op_sel_hi:[1,0]
	v_pk_mul_f32 v[52:53], v[52:53], v[166:167] op_sel_hi:[1,0]
	v_cvt_pk_bf16_f32 v172, v58, v59
	v_cvt_pk_bf16_f32 v173, v60, v61
	v_cvt_pk_bf16_f32 v174, v50, v51
	v_cvt_pk_bf16_f32 v175, v52, v53
	global_store_dwordx4 v131, v[172:175], s[2:3] offset:256
	s_waitcnt vmcnt(12)
	v_add_f32_e32 v164, v152, v153
	v_add_f32_e32 v165, v154, v155
	v_add_f32_e32 v164, v164, v165
	v_fmamk_f32 v164, v164, 0x3b800000, v222
	v_mul_f32_e32 v165, 0x4b800000, v164
	v_cmp_gt_f32_e32 vcc, s92, v164
	s_nop 1
	v_cndmask_b32_e32 v164, v164, v165, vcc
	v_rsq_f32_e32 v164, v164
	s_nop 0
	v_mul_f32_e32 v165, 0x45800000, v164
	v_cndmask_b32_e32 v166, v164, v165, vcc
	v_add_u32_e32 v131, 0x48000, v130
	v_pk_mul_f32 v[46:47], v[46:47], v[166:167] op_sel_hi:[1,0]
	v_pk_mul_f32 v[48:49], v[48:49], v[166:167] op_sel_hi:[1,0]
	v_pk_mul_f32 v[38:39], v[38:39], v[166:167] op_sel_hi:[1,0]
	v_pk_mul_f32 v[40:41], v[40:41], v[166:167] op_sel_hi:[1,0]
	v_cvt_pk_bf16_f32 v176, v46, v47
	v_cvt_pk_bf16_f32 v177, v48, v49
	v_cvt_pk_bf16_f32 v178, v38, v39
	v_cvt_pk_bf16_f32 v179, v40, v41
	global_store_dwordx4 v131, v[176:179], s[2:3]
	v_pk_mul_f32 v[42:43], v[42:43], v[166:167] op_sel_hi:[1,0]
	v_pk_mul_f32 v[44:45], v[44:45], v[166:167] op_sel_hi:[1,0]
	v_pk_mul_f32 v[34:35], v[34:35], v[166:167] op_sel_hi:[1,0]
	v_pk_mul_f32 v[36:37], v[36:37], v[166:167] op_sel_hi:[1,0]
	v_cvt_pk_bf16_f32 v200, v42, v43
	v_cvt_pk_bf16_f32 v201, v44, v45
	v_cvt_pk_bf16_f32 v202, v34, v35
	v_cvt_pk_bf16_f32 v203, v36, v37
	global_store_dwordx4 v131, v[200:203], s[2:3] offset:256
	s_waitcnt vmcnt(13)
	v_add_f32_e32 v164, v156, v157
	v_add_f32_e32 v165, v158, v159
	v_add_f32_e32 v164, v164, v165
	v_fmamk_f32 v164, v164, 0x3b800000, v222
	v_mul_f32_e32 v165, 0x4b800000, v164
	v_cmp_gt_f32_e32 vcc, s92, v164
	s_nop 1
	v_cndmask_b32_e32 v164, v164, v165, vcc
	v_rsq_f32_e32 v164, v164
	s_nop 0
	v_mul_f32_e32 v165, 0x45800000, v164
	v_cndmask_b32_e32 v166, v164, v165, vcc
	v_add_u32_e32 v131, 0x50000, v130
	v_pk_mul_f32 v[30:31], v[30:31], v[166:167] op_sel_hi:[1,0]
	v_pk_mul_f32 v[32:33], v[32:33], v[166:167] op_sel_hi:[1,0]
	v_pk_mul_f32 v[22:23], v[22:23], v[166:167] op_sel_hi:[1,0]
	v_pk_mul_f32 v[24:25], v[24:25], v[166:167] op_sel_hi:[1,0]
	v_cvt_pk_bf16_f32 v168, v30, v31
	v_cvt_pk_bf16_f32 v169, v32, v33
	v_cvt_pk_bf16_f32 v170, v22, v23
	v_cvt_pk_bf16_f32 v171, v24, v25
	global_store_dwordx4 v131, v[168:171], s[2:3]
	v_pk_mul_f32 v[26:27], v[26:27], v[166:167] op_sel_hi:[1,0]
	v_pk_mul_f32 v[28:29], v[28:29], v[166:167] op_sel_hi:[1,0]
	v_pk_mul_f32 v[18:19], v[18:19], v[166:167] op_sel_hi:[1,0]
	v_pk_mul_f32 v[20:21], v[20:21], v[166:167] op_sel_hi:[1,0]
	v_cvt_pk_bf16_f32 v172, v26, v27
	v_cvt_pk_bf16_f32 v173, v28, v29
	v_cvt_pk_bf16_f32 v174, v18, v19
	v_cvt_pk_bf16_f32 v175, v20, v21
	global_store_dwordx4 v131, v[172:175], s[2:3] offset:256
	s_waitcnt vmcnt(14)
	v_add_f32_e32 v164, v160, v161
	v_add_f32_e32 v165, v162, v163
	v_add_f32_e32 v164, v164, v165
	v_fmamk_f32 v164, v164, 0x3b800000, v222
	v_mul_f32_e32 v165, 0x4b800000, v164
	v_cmp_gt_f32_e32 vcc, s92, v164
	s_nop 1
	v_cndmask_b32_e32 v164, v164, v165, vcc
	v_rsq_f32_e32 v164, v164
	s_nop 0
	v_mul_f32_e32 v165, 0x45800000, v164
	v_cndmask_b32_e32 v166, v164, v165, vcc
	v_add_u32_e32 v131, 0x58000, v130
	v_pk_mul_f32 v[14:15], v[14:15], v[166:167] op_sel_hi:[1,0]
	v_pk_mul_f32 v[16:17], v[16:17], v[166:167] op_sel_hi:[1,0]
	v_pk_mul_f32 v[6:7], v[6:7], v[166:167] op_sel_hi:[1,0]
	v_pk_mul_f32 v[8:9], v[8:9], v[166:167] op_sel_hi:[1,0]
	v_cvt_pk_bf16_f32 v176, v14, v15
	v_cvt_pk_bf16_f32 v177, v16, v17
	v_cvt_pk_bf16_f32 v178, v6, v7
	v_cvt_pk_bf16_f32 v179, v8, v9
	global_store_dwordx4 v131, v[176:179], s[2:3]
	v_pk_mul_f32 v[10:11], v[10:11], v[166:167] op_sel_hi:[1,0]
	v_pk_mul_f32 v[12:13], v[12:13], v[166:167] op_sel_hi:[1,0]
	v_pk_mul_f32 v[2:3], v[2:3], v[166:167] op_sel_hi:[1,0]
	v_pk_mul_f32 v[4:5], v[4:5], v[166:167] op_sel_hi:[1,0]
	v_cvt_pk_bf16_f32 v200, v10, v11
	v_cvt_pk_bf16_f32 v201, v12, v13
	v_cvt_pk_bf16_f32 v202, v2, v3
	v_cvt_pk_bf16_f32 v203, v4, v5
	global_store_dwordx4 v131, v[200:203], s[2:3] offset:256
	s_mov_b64 s[2:3], 0
